# P7 V-part (swapped tiles) epilogue rewritten by hand: one uniform prompt/sample branch instead of 64 exec-masked stores, merged 16-byte stores
# speedup vs baseline: 1.0014x; 1.0014x over previous
.LBB0_1012:
	s_andn2_b64 vcc, exec, s[0:1]
	s_cbranch_vccnz .LBB0_1142
	v_and_b32_e32 v210, 15, v198
	v_lshrrev_b32_e32 v211, 8, v198
	v_lshl_add_u32 v210, v211, 6, v210
	v_bfe_u32 v211, v198, 4, 2
	v_bfe_u32 v212, v198, 6, 2
	s_sub_u32 s8, s38, 8
	s_lshr_b32 s9, s8, 1
	s_and_b32 s8, s8, 1
	s_cmp_lt_u32 s40, 64
	s_cbranch_scc0 .Lv7_sample
	v_lshlrev_b32_e32 v208, 13, v210
	v_lshl_add_u32 v208, v212, 6, v208
	v_lshl_add_u32 v208, v211, 3, v208
	v_and_b32_e32 v211, 1, v211
	v_mul_u32_u24_e32 v211, 24, v211
	v_add_u32_e32 v208, v208, v211
	s_lshr_b32 s10, s40, 4
	s_lshl_b32 s10, s10, 2
	s_add_u32 s10, s10, s9
	s_lshl_b32 s10, s10, 22
	s_lshl_b32 s8, s8, 21
	s_add_u32 s10, s10, s8
	s_and_b32 s8, s40, 15
	s_lshl_b32 s8, s8, 9
	s_add_u32 s10, s10, s8
	s_add_u32 s10, s10, 0x23002800
	s_add_u32 s60, s94, s10
	s_addc_u32 s61, s95, 0
	v_cvt_pk_bf16_f32 v200, v124, v125
	v_cvt_pk_bf16_f32 v201, v126, v127
	v_cvt_pk_bf16_f32 v202, v116, v117
	v_cvt_pk_bf16_f32 v203, v118, v119
	s_nop 1
	v_permlane16_swap_b32_e32 v200, v202
	v_permlane16_swap_b32_e32 v201, v203
	global_store_dwordx4 v208, v[200:203], s[60:61]
	v_cvt_pk_bf16_f32 v204, v120, v121
	v_cvt_pk_bf16_f32 v205, v122, v123
	v_cvt_pk_bf16_f32 v206, v112, v113
	v_cvt_pk_bf16_f32 v207, v114, v115
	s_nop 1
	v_permlane16_swap_b32_e32 v204, v206
	v_permlane16_swap_b32_e32 v205, v207
	global_store_dwordx4 v208, v[204:207], s[60:61] offset:256
	v_cvt_pk_bf16_f32 v200, v108, v109
	v_cvt_pk_bf16_f32 v201, v110, v111
	v_cvt_pk_bf16_f32 v202, v100, v101
	v_cvt_pk_bf16_f32 v203, v102, v103
	s_add_u32 s62, s60, 0x20000
	s_addc_u32 s63, s61, 0
	v_permlane16_swap_b32_e32 v200, v202
	v_permlane16_swap_b32_e32 v201, v203
	global_store_dwordx4 v208, v[200:203], s[62:63]
	v_cvt_pk_bf16_f32 v204, v104, v105
	v_cvt_pk_bf16_f32 v205, v106, v107
	v_cvt_pk_bf16_f32 v206, v96, v97
	v_cvt_pk_bf16_f32 v207, v98, v99
	s_add_u32 s62, s60, 0x20000
	s_addc_u32 s63, s61, 0
	v_permlane16_swap_b32_e32 v204, v206
	v_permlane16_swap_b32_e32 v205, v207
	global_store_dwordx4 v208, v[204:207], s[62:63] offset:256
	v_cvt_pk_bf16_f32 v200, v92, v93
	v_cvt_pk_bf16_f32 v201, v94, v95
	v_cvt_pk_bf16_f32 v202, v84, v85
	v_cvt_pk_bf16_f32 v203, v86, v87
	s_add_u32 s62, s60, 0x40000
	s_addc_u32 s63, s61, 0
	v_permlane16_swap_b32_e32 v200, v202
	v_permlane16_swap_b32_e32 v201, v203
	global_store_dwordx4 v208, v[200:203], s[62:63]
	v_cvt_pk_bf16_f32 v204, v88, v89
	v_cvt_pk_bf16_f32 v205, v90, v91
	v_cvt_pk_bf16_f32 v206, v80, v81
	v_cvt_pk_bf16_f32 v207, v82, v83
	s_add_u32 s62, s60, 0x40000
	s_addc_u32 s63, s61, 0
	v_permlane16_swap_b32_e32 v204, v206
	v_permlane16_swap_b32_e32 v205, v207
	global_store_dwordx4 v208, v[204:207], s[62:63] offset:256
	v_cvt_pk_bf16_f32 v200, v76, v77
	v_cvt_pk_bf16_f32 v201, v78, v79
	v_cvt_pk_bf16_f32 v202, v68, v69
	v_cvt_pk_bf16_f32 v203, v70, v71
	s_add_u32 s62, s60, 0x60000
	s_addc_u32 s63, s61, 0
	v_permlane16_swap_b32_e32 v200, v202
	v_permlane16_swap_b32_e32 v201, v203
	global_store_dwordx4 v208, v[200:203], s[62:63]
	v_cvt_pk_bf16_f32 v204, v72, v73
	v_cvt_pk_bf16_f32 v205, v74, v75
	v_cvt_pk_bf16_f32 v206, v64, v65
	v_cvt_pk_bf16_f32 v207, v66, v67
	s_add_u32 s62, s60, 0x60000
	s_addc_u32 s63, s61, 0
	v_permlane16_swap_b32_e32 v204, v206
	v_permlane16_swap_b32_e32 v205, v207
	global_store_dwordx4 v208, v[204:207], s[62:63] offset:256
	v_cvt_pk_bf16_f32 v200, v60, v61
	v_cvt_pk_bf16_f32 v201, v62, v63
	v_cvt_pk_bf16_f32 v202, v52, v53
	v_cvt_pk_bf16_f32 v203, v54, v55
	s_add_u32 s62, s60, 0x100000
	s_addc_u32 s63, s61, 0
	v_permlane16_swap_b32_e32 v200, v202
	v_permlane16_swap_b32_e32 v201, v203
	global_store_dwordx4 v208, v[200:203], s[62:63]
	v_cvt_pk_bf16_f32 v204, v56, v57
	v_cvt_pk_bf16_f32 v205, v58, v59
	v_cvt_pk_bf16_f32 v206, v48, v49
	v_cvt_pk_bf16_f32 v207, v50, v51
	s_add_u32 s62, s60, 0x100000
	s_addc_u32 s63, s61, 0
	v_permlane16_swap_b32_e32 v204, v206
	v_permlane16_swap_b32_e32 v205, v207
	global_store_dwordx4 v208, v[204:207], s[62:63] offset:256
	v_cvt_pk_bf16_f32 v200, v44, v45
	v_cvt_pk_bf16_f32 v201, v46, v47
	v_cvt_pk_bf16_f32 v202, v36, v37
	v_cvt_pk_bf16_f32 v203, v38, v39
	s_add_u32 s62, s60, 0x120000
	s_addc_u32 s63, s61, 0
	v_permlane16_swap_b32_e32 v200, v202
	v_permlane16_swap_b32_e32 v201, v203
	global_store_dwordx4 v208, v[200:203], s[62:63]
	v_cvt_pk_bf16_f32 v204, v40, v41
	v_cvt_pk_bf16_f32 v205, v42, v43
	v_cvt_pk_bf16_f32 v206, v32, v33
	v_cvt_pk_bf16_f32 v207, v34, v35
	s_add_u32 s62, s60, 0x120000
	s_addc_u32 s63, s61, 0
	v_permlane16_swap_b32_e32 v204, v206
	v_permlane16_swap_b32_e32 v205, v207
	global_store_dwordx4 v208, v[204:207], s[62:63] offset:256
	v_cvt_pk_bf16_f32 v200, v28, v29
	v_cvt_pk_bf16_f32 v201, v30, v31
	v_cvt_pk_bf16_f32 v202, v20, v21
	v_cvt_pk_bf16_f32 v203, v22, v23
	s_add_u32 s62, s60, 0x140000
	s_addc_u32 s63, s61, 0
	v_permlane16_swap_b32_e32 v200, v202
	v_permlane16_swap_b32_e32 v201, v203
	global_store_dwordx4 v208, v[200:203], s[62:63]
	v_cvt_pk_bf16_f32 v204, v24, v25
	v_cvt_pk_bf16_f32 v205, v26, v27
	v_cvt_pk_bf16_f32 v206, v16, v17
	v_cvt_pk_bf16_f32 v207, v18, v19
	s_add_u32 s62, s60, 0x140000
	s_addc_u32 s63, s61, 0
	v_permlane16_swap_b32_e32 v204, v206
	v_permlane16_swap_b32_e32 v205, v207
	global_store_dwordx4 v208, v[204:207], s[62:63] offset:256
	v_cvt_pk_bf16_f32 v200, v12, v13
	v_cvt_pk_bf16_f32 v201, v14, v15
	v_cvt_pk_bf16_f32 v202, v4, v5
	v_cvt_pk_bf16_f32 v203, v6, v7
	s_add_u32 s62, s60, 0x160000
	s_addc_u32 s63, s61, 0
	v_permlane16_swap_b32_e32 v200, v202
	v_permlane16_swap_b32_e32 v201, v203
	global_store_dwordx4 v208, v[200:203], s[62:63]
	v_cvt_pk_bf16_f32 v204, v8, v9
	v_cvt_pk_bf16_f32 v205, v10, v11
	v_cvt_pk_bf16_f32 v206, v0, v1
	v_cvt_pk_bf16_f32 v207, v2, v3
	s_add_u32 s62, s60, 0x160000
	s_addc_u32 s63, s61, 0
	v_permlane16_swap_b32_e32 v204, v206
	v_permlane16_swap_b32_e32 v205, v207
	global_store_dwordx4 v208, v[204:207], s[62:63] offset:256
	s_branch .Lv7_done
.Lv7_sample:
	v_lshlrev_b32_e32 v209, 4, v210
	v_lshl_add_u32 v209, v212, 17, v209
	v_lshrrev_b32_e32 v212, 1, v211
	v_lshl_add_u32 v209, v212, 15, v209
	v_and_b32_e32 v211, 1, v211
	v_lshl_add_u32 v209, v211, 16, v209
	s_sub_u32 s10, s40, 64
	s_lshl_b32 s10, s10, 20
	s_lshl_b32 s9, s9, 13
	s_add_u32 s10, s10, s9
	s_lshl_b32 s8, s8, 12
	s_add_u32 s10, s10, s8
	s_add_u32 s10, s10, 0x27002800
	s_add_u32 s60, s94, s10
	s_addc_u32 s61, s95, 0
	v_cvt_pk_bf16_f32 v200, v124, v125
	v_cvt_pk_bf16_f32 v201, v126, v127
	v_cvt_pk_bf16_f32 v202, v116, v117
	v_cvt_pk_bf16_f32 v203, v118, v119
	s_nop 1
	v_permlane16_swap_b32_e32 v200, v202
	v_permlane16_swap_b32_e32 v201, v203
	global_store_dwordx4 v209, v[200:203], s[60:61]
	v_cvt_pk_bf16_f32 v204, v120, v121
	v_cvt_pk_bf16_f32 v205, v122, v123
	v_cvt_pk_bf16_f32 v206, v112, v113
	v_cvt_pk_bf16_f32 v207, v114, v115
	s_add_u32 s62, s60, 0x80000
	s_addc_u32 s63, s61, 0
	v_permlane16_swap_b32_e32 v204, v206
	v_permlane16_swap_b32_e32 v205, v207
	global_store_dwordx4 v209, v[204:207], s[62:63]
	v_cvt_pk_bf16_f32 v200, v108, v109
	v_cvt_pk_bf16_f32 v201, v110, v111
	v_cvt_pk_bf16_f32 v202, v100, v101
	v_cvt_pk_bf16_f32 v203, v102, v103
	s_add_u32 s62, s60, 0x100
	s_addc_u32 s63, s61, 0
	v_permlane16_swap_b32_e32 v200, v202
	v_permlane16_swap_b32_e32 v201, v203
	global_store_dwordx4 v209, v[200:203], s[62:63]
	v_cvt_pk_bf16_f32 v204, v104, v105
	v_cvt_pk_bf16_f32 v205, v106, v107
	v_cvt_pk_bf16_f32 v206, v96, v97
	v_cvt_pk_bf16_f32 v207, v98, v99
	s_add_u32 s62, s60, 0x80100
	s_addc_u32 s63, s61, 0
	v_permlane16_swap_b32_e32 v204, v206
	v_permlane16_swap_b32_e32 v205, v207
	global_store_dwordx4 v209, v[204:207], s[62:63]
	v_cvt_pk_bf16_f32 v200, v92, v93
	v_cvt_pk_bf16_f32 v201, v94, v95
	v_cvt_pk_bf16_f32 v202, v84, v85
	v_cvt_pk_bf16_f32 v203, v86, v87
	s_add_u32 s62, s60, 0x200
	s_addc_u32 s63, s61, 0
	v_permlane16_swap_b32_e32 v200, v202
	v_permlane16_swap_b32_e32 v201, v203
	global_store_dwordx4 v209, v[200:203], s[62:63]
	v_cvt_pk_bf16_f32 v204, v88, v89
	v_cvt_pk_bf16_f32 v205, v90, v91
	v_cvt_pk_bf16_f32 v206, v80, v81
	v_cvt_pk_bf16_f32 v207, v82, v83
	s_add_u32 s62, s60, 0x80200
	s_addc_u32 s63, s61, 0
	v_permlane16_swap_b32_e32 v204, v206
	v_permlane16_swap_b32_e32 v205, v207
	global_store_dwordx4 v209, v[204:207], s[62:63]
	v_cvt_pk_bf16_f32 v200, v76, v77
	v_cvt_pk_bf16_f32 v201, v78, v79
	v_cvt_pk_bf16_f32 v202, v68, v69
	v_cvt_pk_bf16_f32 v203, v70, v71
	s_add_u32 s62, s60, 0x300
	s_addc_u32 s63, s61, 0
	v_permlane16_swap_b32_e32 v200, v202
	v_permlane16_swap_b32_e32 v201, v203
	global_store_dwordx4 v209, v[200:203], s[62:63]
	v_cvt_pk_bf16_f32 v204, v72, v73
	v_cvt_pk_bf16_f32 v205, v74, v75
	v_cvt_pk_bf16_f32 v206, v64, v65
	v_cvt_pk_bf16_f32 v207, v66, v67
	s_add_u32 s62, s60, 0x80300
	s_addc_u32 s63, s61, 0
	v_permlane16_swap_b32_e32 v204, v206
	v_permlane16_swap_b32_e32 v205, v207
	global_store_dwordx4 v209, v[204:207], s[62:63]
	v_cvt_pk_bf16_f32 v200, v60, v61
	v_cvt_pk_bf16_f32 v201, v62, v63
	v_cvt_pk_bf16_f32 v202, v52, v53
	v_cvt_pk_bf16_f32 v203, v54, v55
	s_add_u32 s62, s60, 0x800
	s_addc_u32 s63, s61, 0
	v_permlane16_swap_b32_e32 v200, v202
	v_permlane16_swap_b32_e32 v201, v203
	global_store_dwordx4 v209, v[200:203], s[62:63]
	v_cvt_pk_bf16_f32 v204, v56, v57
	v_cvt_pk_bf16_f32 v205, v58, v59
	v_cvt_pk_bf16_f32 v206, v48, v49
	v_cvt_pk_bf16_f32 v207, v50, v51
	s_add_u32 s62, s60, 0x80800
	s_addc_u32 s63, s61, 0
	v_permlane16_swap_b32_e32 v204, v206
	v_permlane16_swap_b32_e32 v205, v207
	global_store_dwordx4 v209, v[204:207], s[62:63]
	v_cvt_pk_bf16_f32 v200, v44, v45
	v_cvt_pk_bf16_f32 v201, v46, v47
	v_cvt_pk_bf16_f32 v202, v36, v37
	v_cvt_pk_bf16_f32 v203, v38, v39
	s_add_u32 s62, s60, 0x900
	s_addc_u32 s63, s61, 0
	v_permlane16_swap_b32_e32 v200, v202
	v_permlane16_swap_b32_e32 v201, v203
	global_store_dwordx4 v209, v[200:203], s[62:63]
	v_cvt_pk_bf16_f32 v204, v40, v41
	v_cvt_pk_bf16_f32 v205, v42, v43
	v_cvt_pk_bf16_f32 v206, v32, v33
	v_cvt_pk_bf16_f32 v207, v34, v35
	s_add_u32 s62, s60, 0x80900
	s_addc_u32 s63, s61, 0
	v_permlane16_swap_b32_e32 v204, v206
	v_permlane16_swap_b32_e32 v205, v207
	global_store_dwordx4 v209, v[204:207], s[62:63]
	v_cvt_pk_bf16_f32 v200, v28, v29
	v_cvt_pk_bf16_f32 v201, v30, v31
	v_cvt_pk_bf16_f32 v202, v20, v21
	v_cvt_pk_bf16_f32 v203, v22, v23
	s_add_u32 s62, s60, 0xa00
	s_addc_u32 s63, s61, 0
	v_permlane16_swap_b32_e32 v200, v202
	v_permlane16_swap_b32_e32 v201, v203
	global_store_dwordx4 v209, v[200:203], s[62:63]
	v_cvt_pk_bf16_f32 v204, v24, v25
	v_cvt_pk_bf16_f32 v205, v26, v27
	v_cvt_pk_bf16_f32 v206, v16, v17
	v_cvt_pk_bf16_f32 v207, v18, v19
	s_add_u32 s62, s60, 0x80a00
	s_addc_u32 s63, s61, 0
	v_permlane16_swap_b32_e32 v204, v206
	v_permlane16_swap_b32_e32 v205, v207
	global_store_dwordx4 v209, v[204:207], s[62:63]
	v_cvt_pk_bf16_f32 v200, v12, v13
	v_cvt_pk_bf16_f32 v201, v14, v15
	v_cvt_pk_bf16_f32 v202, v4, v5
	v_cvt_pk_bf16_f32 v203, v6, v7
	s_add_u32 s62, s60, 0xb00
	s_addc_u32 s63, s61, 0
	v_permlane16_swap_b32_e32 v200, v202
	v_permlane16_swap_b32_e32 v201, v203
	global_store_dwordx4 v209, v[200:203], s[62:63]
	v_cvt_pk_bf16_f32 v204, v8, v9
	v_cvt_pk_bf16_f32 v205, v10, v11
	v_cvt_pk_bf16_f32 v206, v0, v1
	v_cvt_pk_bf16_f32 v207, v2, v3
	s_add_u32 s62, s60, 0x80b00
	s_addc_u32 s63, s61, 0
	v_permlane16_swap_b32_e32 v204, v206
	v_permlane16_swap_b32_e32 v205, v207
	global_store_dwordx4 v209, v[204:207], s[62:63]
.Lv7_done:
.LBB0_1142:
	s_mov_b64 s[0:1], 0
